# NSA tile epilogue: 16-step load/wait/store ladder de-serialised (all partial-result loads issued up front, one wait)
# baseline (speedup 1.0000x reference)
.LBB0_1467:
	v_mov_b32_e32 v3, v220
	s_add_i32 s6, s6, s74
	v_ashrrev_i32_e32 v0, 6, v3
	v_lshl_add_u32 v1, v0, 3, s76
	v_lshrrev_b32_e32 v2, 2, v3
	v_and_or_b32 v2, v2, 3, v1
	v_and_or_b32 v12, v3, 3, s7
	v_mul_lo_u32 v1, v2, 48
	v_mad_u32_u24 v6, v12, 3, v1
	v_ashrrev_i32_e32 v7, 31, v6
	v_lshl_add_u64 v[4:5], v[6:7], 2, s[62:63]
	global_load_dword v7, v[4:5], off offset:8
	v_ashrrev_i32_e32 v1, 31, v0
	v_lshlrev_b64 v[0:1], 6, v[0:1]
	v_lshl_add_u64 v[0:1], v[0:1], 0, s[58:59]
	v_and_or_b32 v0, v3, 63, v0
	v_lshlrev_b64 v[0:1], 8, v[0:1]
	v_lshl_add_u64 v[0:1], s[64:65], 0, v[0:1]
	global_load_dwordx4 v[8:11], v[0:1], off
	global_load_dwordx4 v[20:23], v[0:1], off offset:16
	global_load_dwordx4 v[24:27], v[0:1], off offset:32
	global_load_dwordx4 v[28:31], v[0:1], off offset:48
	global_load_dwordx4 v[32:35], v[0:1], off offset:64
	global_load_dwordx4 v[36:39], v[0:1], off offset:80
	global_load_dwordx4 v[40:43], v[0:1], off offset:96
	global_load_dwordx4 v[44:47], v[0:1], off offset:112
	global_load_dwordx4 v[48:51], v[0:1], off offset:128
	global_load_dwordx4 v[116:119], v[0:1], off offset:144
	global_load_dwordx4 v[120:123], v[0:1], off offset:160
	global_load_dwordx4 v[124:127], v[0:1], off offset:176
	global_load_dwordx4 v[128:131], v[0:1], off offset:192
	global_load_dwordx4 v[132:135], v[0:1], off offset:208
	global_load_dwordx4 v[136:139], v[0:1], off offset:224
	global_load_dwordx4 v[140:143], v[0:1], off offset:240
	v_add_u32_e32 v144, 0xc0, v6
	v_ashrrev_i32_e32 v145, 31, v144
	v_lshl_add_u64 v[144:145], v[144:145], 2, s[62:63]
	global_load_dword v146, v[144:145], off offset:8
	v_mov_b32_e32 v4, v195
	s_nop 1
	v_permlane32_swap_b32_e32 v195, v4
	v_add_f32_e32 v13, v195, v4
	v_lshlrev_b32_e32 v16, 8, v12
	v_mov_b32_e32 v12, v13
	v_lshrrev_b32_e32 v3, 1, v3
	s_nop 0
	v_permlane16_swap_b32_e32 v13, v12
	v_lshl_add_u64 v[4:5], s[60:61], 0, v[16:17]
	v_and_b32_e32 v16, 24, v3
	v_add_f32_e32 v14, v13, v12
	v_ashrrev_i32_e32 v3, 31, v2
	v_lshlrev_b64 v[12:13], 12, v[2:3]
	v_lshl_add_u64 v[4:5], v[4:5], 0, v[16:17]
	v_lshl_add_u64 v[12:13], v[4:5], 0, v[12:13]
	v_add_u32_e32 v6, 0xc0, v6
	v_or_b32_e32 v2, 4, v2
	s_cmpk_lt_i32 s6, 0x1000
	s_waitcnt vmcnt(17)
	v_div_scale_f32 v3, s[0:1], v14, v14, v7
	v_rcp_f32_e32 v15, v3
	v_div_scale_f32 v16, vcc, v7, v14, v7
	v_fma_f32 v18, -v3, v15, 1.0
	v_fmac_f32_e32 v15, v18, v15
	v_mul_f32_e32 v18, v16, v15
	v_fma_f32 v19, -v3, v18, v16
	v_fmac_f32_e32 v18, v19, v15
	v_fma_f32 v3, -v3, v18, v16
	v_div_fmas_f32 v3, v3, v15, v18
	v_div_fixup_f32 v14, v3, v14, v7
	s_waitcnt vmcnt(0)
	v_pk_fma_f32 v[8:9], v[112:113], v[14:15], v[8:9] op_sel_hi:[1,0,1]
	v_pk_fma_f32 v[10:11], v[114:115], v[14:15], v[10:11] op_sel_hi:[1,0,1]
	v_and_b32_sdwa v7, v8, v174 dst_sel:DWORD dst_unused:UNUSED_PAD src0_sel:WORD_1 src1_sel:DWORD
	v_and_b32_sdwa v15, v11, v174 dst_sel:DWORD dst_unused:UNUSED_PAD src0_sel:WORD_1 src1_sel:DWORD
	v_and_b32_sdwa v16, v9, v174 dst_sel:DWORD dst_unused:UNUSED_PAD src0_sel:WORD_1 src1_sel:DWORD
	v_and_b32_sdwa v3, v10, v174 dst_sel:DWORD dst_unused:UNUSED_PAD src0_sel:WORD_1 src1_sel:DWORD
	v_add3_u32 v7, v8, v7, s9
	v_add3_u32 v8, v11, v15, s9
	v_add3_u32 v9, v9, v16, s9
	v_add3_u32 v3, v10, v3, s9
	v_and_b32_e32 v8, 0xffff0000, v8
	v_and_b32_e32 v10, 0xffff0000, v9
	v_or_b32_sdwa v9, v8, v3 dst_sel:DWORD dst_unused:UNUSED_PAD src0_sel:DWORD src1_sel:WORD_1
	v_or_b32_sdwa v8, v10, v7 dst_sel:DWORD dst_unused:UNUSED_PAD src0_sel:DWORD src1_sel:WORD_1
	global_store_dwordx2 v[12:13], v[8:9], off
	v_mov_b64_e32 v[8:9], v[20:21]
	v_mov_b64_e32 v[10:11], v[22:23]
	v_pk_fma_f32 v[10:11], v[110:111], v[14:15], v[10:11] op_sel_hi:[1,0,1]
	v_pk_fma_f32 v[8:9], v[108:109], v[14:15], v[8:9] op_sel_hi:[1,0,1]
	v_and_b32_sdwa v15, v11, v174 dst_sel:DWORD dst_unused:UNUSED_PAD src0_sel:WORD_1 src1_sel:DWORD
	v_and_b32_sdwa v7, v8, v174 dst_sel:DWORD dst_unused:UNUSED_PAD src0_sel:WORD_1 src1_sel:DWORD
	v_and_b32_sdwa v16, v9, v174 dst_sel:DWORD dst_unused:UNUSED_PAD src0_sel:WORD_1 src1_sel:DWORD
	v_and_b32_sdwa v3, v10, v174 dst_sel:DWORD dst_unused:UNUSED_PAD src0_sel:WORD_1 src1_sel:DWORD
	v_add3_u32 v7, v8, v7, s9
	v_add3_u32 v8, v11, v15, s9
	v_add3_u32 v9, v9, v16, s9
	v_add3_u32 v3, v10, v3, s9
	v_and_b32_e32 v8, 0xffff0000, v8
	v_and_b32_e32 v10, 0xffff0000, v9
	v_or_b32_sdwa v9, v8, v3 dst_sel:DWORD dst_unused:UNUSED_PAD src0_sel:DWORD src1_sel:WORD_1
	v_or_b32_sdwa v8, v10, v7 dst_sel:DWORD dst_unused:UNUSED_PAD src0_sel:DWORD src1_sel:WORD_1
	global_store_dwordx2 v[12:13], v[8:9], off offset:32
	v_mov_b64_e32 v[8:9], v[24:25]
	v_mov_b64_e32 v[10:11], v[26:27]
	v_pk_fma_f32 v[10:11], v[106:107], v[14:15], v[10:11] op_sel_hi:[1,0,1]
	v_pk_fma_f32 v[8:9], v[104:105], v[14:15], v[8:9] op_sel_hi:[1,0,1]
	v_and_b32_sdwa v15, v11, v174 dst_sel:DWORD dst_unused:UNUSED_PAD src0_sel:WORD_1 src1_sel:DWORD
	v_and_b32_sdwa v7, v8, v174 dst_sel:DWORD dst_unused:UNUSED_PAD src0_sel:WORD_1 src1_sel:DWORD
	v_and_b32_sdwa v16, v9, v174 dst_sel:DWORD dst_unused:UNUSED_PAD src0_sel:WORD_1 src1_sel:DWORD
	v_and_b32_sdwa v3, v10, v174 dst_sel:DWORD dst_unused:UNUSED_PAD src0_sel:WORD_1 src1_sel:DWORD
	v_add3_u32 v7, v8, v7, s9
	v_add3_u32 v8, v11, v15, s9
	v_add3_u32 v9, v9, v16, s9
	v_add3_u32 v3, v10, v3, s9
	v_and_b32_e32 v8, 0xffff0000, v8
	v_and_b32_e32 v10, 0xffff0000, v9
	v_or_b32_sdwa v9, v8, v3 dst_sel:DWORD dst_unused:UNUSED_PAD src0_sel:DWORD src1_sel:WORD_1
	v_or_b32_sdwa v8, v10, v7 dst_sel:DWORD dst_unused:UNUSED_PAD src0_sel:DWORD src1_sel:WORD_1
	global_store_dwordx2 v[12:13], v[8:9], off offset:64
	v_mov_b64_e32 v[8:9], v[28:29]
	v_mov_b64_e32 v[10:11], v[30:31]
	v_pk_fma_f32 v[10:11], v[102:103], v[14:15], v[10:11] op_sel_hi:[1,0,1]
	v_pk_fma_f32 v[8:9], v[100:101], v[14:15], v[8:9] op_sel_hi:[1,0,1]
	v_and_b32_sdwa v15, v11, v174 dst_sel:DWORD dst_unused:UNUSED_PAD src0_sel:WORD_1 src1_sel:DWORD
	v_and_b32_sdwa v7, v8, v174 dst_sel:DWORD dst_unused:UNUSED_PAD src0_sel:WORD_1 src1_sel:DWORD
	v_and_b32_sdwa v16, v9, v174 dst_sel:DWORD dst_unused:UNUSED_PAD src0_sel:WORD_1 src1_sel:DWORD
	v_and_b32_sdwa v3, v10, v174 dst_sel:DWORD dst_unused:UNUSED_PAD src0_sel:WORD_1 src1_sel:DWORD
	v_add3_u32 v7, v8, v7, s9
	v_add3_u32 v8, v11, v15, s9
	v_add3_u32 v9, v9, v16, s9
	v_add3_u32 v3, v10, v3, s9
	v_and_b32_e32 v8, 0xffff0000, v8
	v_and_b32_e32 v10, 0xffff0000, v9
	v_or_b32_sdwa v9, v8, v3 dst_sel:DWORD dst_unused:UNUSED_PAD src0_sel:DWORD src1_sel:WORD_1
	v_or_b32_sdwa v8, v10, v7 dst_sel:DWORD dst_unused:UNUSED_PAD src0_sel:DWORD src1_sel:WORD_1
	global_store_dwordx2 v[12:13], v[8:9], off offset:96
	v_mov_b64_e32 v[8:9], v[32:33]
	v_mov_b64_e32 v[10:11], v[34:35]
	v_pk_fma_f32 v[10:11], v[98:99], v[14:15], v[10:11] op_sel_hi:[1,0,1]
	v_pk_fma_f32 v[8:9], v[96:97], v[14:15], v[8:9] op_sel_hi:[1,0,1]
	v_and_b32_sdwa v15, v11, v174 dst_sel:DWORD dst_unused:UNUSED_PAD src0_sel:WORD_1 src1_sel:DWORD
	v_and_b32_sdwa v7, v8, v174 dst_sel:DWORD dst_unused:UNUSED_PAD src0_sel:WORD_1 src1_sel:DWORD
	v_and_b32_sdwa v16, v9, v174 dst_sel:DWORD dst_unused:UNUSED_PAD src0_sel:WORD_1 src1_sel:DWORD
	v_and_b32_sdwa v3, v10, v174 dst_sel:DWORD dst_unused:UNUSED_PAD src0_sel:WORD_1 src1_sel:DWORD
	v_add3_u32 v7, v8, v7, s9
	v_add3_u32 v8, v11, v15, s9
	v_add3_u32 v9, v9, v16, s9
	v_add3_u32 v3, v10, v3, s9
	v_and_b32_e32 v8, 0xffff0000, v8
	v_and_b32_e32 v10, 0xffff0000, v9
	v_or_b32_sdwa v9, v8, v3 dst_sel:DWORD dst_unused:UNUSED_PAD src0_sel:DWORD src1_sel:WORD_1
	v_or_b32_sdwa v8, v10, v7 dst_sel:DWORD dst_unused:UNUSED_PAD src0_sel:DWORD src1_sel:WORD_1
	global_store_dwordx2 v[12:13], v[8:9], off offset:128
	v_mov_b64_e32 v[8:9], v[36:37]
	v_mov_b64_e32 v[10:11], v[38:39]
	v_pk_fma_f32 v[10:11], v[94:95], v[14:15], v[10:11] op_sel_hi:[1,0,1]
	v_pk_fma_f32 v[8:9], v[92:93], v[14:15], v[8:9] op_sel_hi:[1,0,1]
	v_and_b32_sdwa v15, v11, v174 dst_sel:DWORD dst_unused:UNUSED_PAD src0_sel:WORD_1 src1_sel:DWORD
	v_and_b32_sdwa v7, v8, v174 dst_sel:DWORD dst_unused:UNUSED_PAD src0_sel:WORD_1 src1_sel:DWORD
	v_and_b32_sdwa v16, v9, v174 dst_sel:DWORD dst_unused:UNUSED_PAD src0_sel:WORD_1 src1_sel:DWORD
	v_and_b32_sdwa v3, v10, v174 dst_sel:DWORD dst_unused:UNUSED_PAD src0_sel:WORD_1 src1_sel:DWORD
	v_add3_u32 v7, v8, v7, s9
	v_add3_u32 v8, v11, v15, s9
	v_add3_u32 v9, v9, v16, s9
	v_add3_u32 v3, v10, v3, s9
	v_and_b32_e32 v8, 0xffff0000, v8
	v_and_b32_e32 v10, 0xffff0000, v9
	v_or_b32_sdwa v9, v8, v3 dst_sel:DWORD dst_unused:UNUSED_PAD src0_sel:DWORD src1_sel:WORD_1
	v_or_b32_sdwa v8, v10, v7 dst_sel:DWORD dst_unused:UNUSED_PAD src0_sel:DWORD src1_sel:WORD_1
	global_store_dwordx2 v[12:13], v[8:9], off offset:160
	v_mov_b64_e32 v[8:9], v[40:41]
	v_mov_b64_e32 v[10:11], v[42:43]
	v_pk_fma_f32 v[10:11], v[90:91], v[14:15], v[10:11] op_sel_hi:[1,0,1]
	v_pk_fma_f32 v[8:9], v[88:89], v[14:15], v[8:9] op_sel_hi:[1,0,1]
	v_and_b32_sdwa v15, v11, v174 dst_sel:DWORD dst_unused:UNUSED_PAD src0_sel:WORD_1 src1_sel:DWORD
	v_and_b32_sdwa v7, v8, v174 dst_sel:DWORD dst_unused:UNUSED_PAD src0_sel:WORD_1 src1_sel:DWORD
	v_and_b32_sdwa v16, v9, v174 dst_sel:DWORD dst_unused:UNUSED_PAD src0_sel:WORD_1 src1_sel:DWORD
	v_and_b32_sdwa v3, v10, v174 dst_sel:DWORD dst_unused:UNUSED_PAD src0_sel:WORD_1 src1_sel:DWORD
	v_add3_u32 v7, v8, v7, s9
	v_add3_u32 v8, v11, v15, s9
	v_add3_u32 v9, v9, v16, s9
	v_add3_u32 v3, v10, v3, s9
	v_and_b32_e32 v8, 0xffff0000, v8
	v_and_b32_e32 v10, 0xffff0000, v9
	v_or_b32_sdwa v9, v8, v3 dst_sel:DWORD dst_unused:UNUSED_PAD src0_sel:DWORD src1_sel:WORD_1
	v_or_b32_sdwa v8, v10, v7 dst_sel:DWORD dst_unused:UNUSED_PAD src0_sel:DWORD src1_sel:WORD_1
	global_store_dwordx2 v[12:13], v[8:9], off offset:192
	v_mov_b64_e32 v[8:9], v[44:45]
	v_mov_b64_e32 v[10:11], v[46:47]
	v_ashrrev_i32_e32 v7, 31, v6
	v_lshl_add_u64 v[6:7], v[6:7], 2, s[62:63]
	v_pk_fma_f32 v[10:11], v[86:87], v[14:15], v[10:11] op_sel_hi:[1,0,1]
	v_pk_fma_f32 v[8:9], v[84:85], v[14:15], v[8:9] op_sel_hi:[1,0,1]
	v_and_b32_sdwa v3, v10, v174 dst_sel:DWORD dst_unused:UNUSED_PAD src0_sel:WORD_1 src1_sel:DWORD
	v_and_b32_sdwa v15, v11, v174 dst_sel:DWORD dst_unused:UNUSED_PAD src0_sel:WORD_1 src1_sel:DWORD
	v_and_b32_sdwa v16, v9, v174 dst_sel:DWORD dst_unused:UNUSED_PAD src0_sel:WORD_1 src1_sel:DWORD
	v_and_b32_sdwa v14, v8, v174 dst_sel:DWORD dst_unused:UNUSED_PAD src0_sel:WORD_1 src1_sel:DWORD
	v_add3_u32 v3, v10, v3, s9
	v_add3_u32 v10, v11, v15, s9
	v_add3_u32 v9, v9, v16, s9
	v_add3_u32 v8, v8, v14, s9
	v_and_b32_e32 v10, 0xffff0000, v10
	v_and_b32_e32 v11, 0xffff0000, v9
	v_or_b32_sdwa v9, v10, v3 dst_sel:DWORD dst_unused:UNUSED_PAD src0_sel:DWORD src1_sel:WORD_1
	v_or_b32_sdwa v8, v11, v8 dst_sel:DWORD dst_unused:UNUSED_PAD src0_sel:DWORD src1_sel:WORD_1
	global_store_dwordx2 v[12:13], v[8:9], off offset:224
	v_mov_b32_e32 v12, v146
	s_nop 0
	v_mov_b64_e32 v[6:7], v[48:49]
	v_mov_b64_e32 v[8:9], v[50:51]
	v_mov_b32_e32 v3, v148
	s_nop 1
	v_permlane32_swap_b32_e32 v148, v3
	v_add_f32_e32 v3, v148, v3
	v_mov_b32_e32 v10, v3
	s_nop 1
	v_permlane16_swap_b32_e32 v3, v10
	v_add_f32_e32 v13, v3, v10
	v_ashrrev_i32_e32 v3, 31, v2
	v_lshlrev_b64 v[2:3], 12, v[2:3]
	v_lshl_add_u64 v[10:11], v[4:5], 0, v[2:3]
	v_div_scale_f32 v14, s[0:1], v13, v13, v12
	v_rcp_f32_e32 v15, v14
	v_div_scale_f32 v2, vcc, v12, v13, v12
	v_fma_f32 v3, -v14, v15, 1.0
	v_fmac_f32_e32 v15, v3, v15
	v_mul_f32_e32 v3, v2, v15
	v_fma_f32 v4, -v14, v3, v2
	v_fmac_f32_e32 v3, v4, v15
	v_fma_f32 v2, -v14, v3, v2
	v_div_fmas_f32 v2, v2, v15, v3
	v_div_fixup_f32 v12, v2, v13, v12
	v_pk_fma_f32 v[2:3], v[80:81], v[12:13], v[6:7] op_sel_hi:[1,0,1]
	v_pk_fma_f32 v[4:5], v[82:83], v[12:13], v[8:9] op_sel_hi:[1,0,1]
	v_and_b32_sdwa v9, v3, v174 dst_sel:DWORD dst_unused:UNUSED_PAD src0_sel:WORD_1 src1_sel:DWORD
	v_and_b32_sdwa v8, v5, v174 dst_sel:DWORD dst_unused:UNUSED_PAD src0_sel:WORD_1 src1_sel:DWORD
	v_and_b32_sdwa v6, v4, v174 dst_sel:DWORD dst_unused:UNUSED_PAD src0_sel:WORD_1 src1_sel:DWORD
	v_and_b32_sdwa v7, v2, v174 dst_sel:DWORD dst_unused:UNUSED_PAD src0_sel:WORD_1 src1_sel:DWORD
	v_add3_u32 v5, v5, v8, s9
	v_add3_u32 v3, v3, v9, s9
	v_add3_u32 v2, v2, v7, s9
	v_add3_u32 v4, v4, v6, s9
	v_and_b32_e32 v5, 0xffff0000, v5
	v_and_b32_e32 v6, 0xffff0000, v3
	v_or_b32_sdwa v3, v5, v4 dst_sel:DWORD dst_unused:UNUSED_PAD src0_sel:DWORD src1_sel:WORD_1
	v_or_b32_sdwa v2, v6, v2 dst_sel:DWORD dst_unused:UNUSED_PAD src0_sel:DWORD src1_sel:WORD_1
	global_store_dwordx2 v[10:11], v[2:3], off
	v_mov_b64_e32 v[2:3], v[116:117]
	v_mov_b64_e32 v[4:5], v[118:119]
	v_pk_fma_f32 v[4:5], v[78:79], v[12:13], v[4:5] op_sel_hi:[1,0,1]
	v_pk_fma_f32 v[2:3], v[76:77], v[12:13], v[2:3] op_sel_hi:[1,0,1]
	v_and_b32_sdwa v8, v5, v174 dst_sel:DWORD dst_unused:UNUSED_PAD src0_sel:WORD_1 src1_sel:DWORD
	v_and_b32_sdwa v9, v3, v174 dst_sel:DWORD dst_unused:UNUSED_PAD src0_sel:WORD_1 src1_sel:DWORD
	v_and_b32_sdwa v6, v4, v174 dst_sel:DWORD dst_unused:UNUSED_PAD src0_sel:WORD_1 src1_sel:DWORD
	v_and_b32_sdwa v7, v2, v174 dst_sel:DWORD dst_unused:UNUSED_PAD src0_sel:WORD_1 src1_sel:DWORD
	v_add3_u32 v5, v5, v8, s9
	v_add3_u32 v3, v3, v9, s9
	v_add3_u32 v2, v2, v7, s9
	v_add3_u32 v4, v4, v6, s9
	v_and_b32_e32 v5, 0xffff0000, v5
	v_and_b32_e32 v6, 0xffff0000, v3
	v_or_b32_sdwa v3, v5, v4 dst_sel:DWORD dst_unused:UNUSED_PAD src0_sel:DWORD src1_sel:WORD_1
	v_or_b32_sdwa v2, v6, v2 dst_sel:DWORD dst_unused:UNUSED_PAD src0_sel:DWORD src1_sel:WORD_1
	global_store_dwordx2 v[10:11], v[2:3], off offset:32
	v_mov_b64_e32 v[2:3], v[120:121]
	v_mov_b64_e32 v[4:5], v[122:123]
	v_pk_fma_f32 v[4:5], v[74:75], v[12:13], v[4:5] op_sel_hi:[1,0,1]
	v_pk_fma_f32 v[2:3], v[72:73], v[12:13], v[2:3] op_sel_hi:[1,0,1]
	v_and_b32_sdwa v8, v5, v174 dst_sel:DWORD dst_unused:UNUSED_PAD src0_sel:WORD_1 src1_sel:DWORD
	v_and_b32_sdwa v9, v3, v174 dst_sel:DWORD dst_unused:UNUSED_PAD src0_sel:WORD_1 src1_sel:DWORD
	v_and_b32_sdwa v6, v4, v174 dst_sel:DWORD dst_unused:UNUSED_PAD src0_sel:WORD_1 src1_sel:DWORD
	v_and_b32_sdwa v7, v2, v174 dst_sel:DWORD dst_unused:UNUSED_PAD src0_sel:WORD_1 src1_sel:DWORD
	v_add3_u32 v5, v5, v8, s9
	v_add3_u32 v3, v3, v9, s9
	v_add3_u32 v2, v2, v7, s9
	v_add3_u32 v4, v4, v6, s9
	v_and_b32_e32 v5, 0xffff0000, v5
	v_and_b32_e32 v6, 0xffff0000, v3
	v_or_b32_sdwa v3, v5, v4 dst_sel:DWORD dst_unused:UNUSED_PAD src0_sel:DWORD src1_sel:WORD_1
	v_or_b32_sdwa v2, v6, v2 dst_sel:DWORD dst_unused:UNUSED_PAD src0_sel:DWORD src1_sel:WORD_1
	global_store_dwordx2 v[10:11], v[2:3], off offset:64
	v_mov_b64_e32 v[2:3], v[124:125]
	v_mov_b64_e32 v[4:5], v[126:127]
	v_pk_fma_f32 v[4:5], v[70:71], v[12:13], v[4:5] op_sel_hi:[1,0,1]
	v_pk_fma_f32 v[2:3], v[68:69], v[12:13], v[2:3] op_sel_hi:[1,0,1]
	v_and_b32_sdwa v8, v5, v174 dst_sel:DWORD dst_unused:UNUSED_PAD src0_sel:WORD_1 src1_sel:DWORD
	v_and_b32_sdwa v9, v3, v174 dst_sel:DWORD dst_unused:UNUSED_PAD src0_sel:WORD_1 src1_sel:DWORD
	v_and_b32_sdwa v6, v4, v174 dst_sel:DWORD dst_unused:UNUSED_PAD src0_sel:WORD_1 src1_sel:DWORD
	v_and_b32_sdwa v7, v2, v174 dst_sel:DWORD dst_unused:UNUSED_PAD src0_sel:WORD_1 src1_sel:DWORD
	v_add3_u32 v5, v5, v8, s9
	v_add3_u32 v3, v3, v9, s9
	v_add3_u32 v2, v2, v7, s9
	v_add3_u32 v4, v4, v6, s9
	v_and_b32_e32 v5, 0xffff0000, v5
	v_and_b32_e32 v6, 0xffff0000, v3
	v_or_b32_sdwa v3, v5, v4 dst_sel:DWORD dst_unused:UNUSED_PAD src0_sel:DWORD src1_sel:WORD_1
	v_or_b32_sdwa v2, v6, v2 dst_sel:DWORD dst_unused:UNUSED_PAD src0_sel:DWORD src1_sel:WORD_1
	global_store_dwordx2 v[10:11], v[2:3], off offset:96
	v_mov_b64_e32 v[2:3], v[128:129]
	v_mov_b64_e32 v[4:5], v[130:131]
	v_pk_fma_f32 v[4:5], v[66:67], v[12:13], v[4:5] op_sel_hi:[1,0,1]
	v_pk_fma_f32 v[2:3], v[64:65], v[12:13], v[2:3] op_sel_hi:[1,0,1]
	v_and_b32_sdwa v8, v5, v174 dst_sel:DWORD dst_unused:UNUSED_PAD src0_sel:WORD_1 src1_sel:DWORD
	v_and_b32_sdwa v9, v3, v174 dst_sel:DWORD dst_unused:UNUSED_PAD src0_sel:WORD_1 src1_sel:DWORD
	v_and_b32_sdwa v6, v4, v174 dst_sel:DWORD dst_unused:UNUSED_PAD src0_sel:WORD_1 src1_sel:DWORD
	v_and_b32_sdwa v7, v2, v174 dst_sel:DWORD dst_unused:UNUSED_PAD src0_sel:WORD_1 src1_sel:DWORD
	v_add3_u32 v5, v5, v8, s9
	v_add3_u32 v3, v3, v9, s9
	v_add3_u32 v2, v2, v7, s9
	v_add3_u32 v4, v4, v6, s9
	v_and_b32_e32 v5, 0xffff0000, v5
	v_and_b32_e32 v6, 0xffff0000, v3
	v_or_b32_sdwa v3, v5, v4 dst_sel:DWORD dst_unused:UNUSED_PAD src0_sel:DWORD src1_sel:WORD_1
	v_or_b32_sdwa v2, v6, v2 dst_sel:DWORD dst_unused:UNUSED_PAD src0_sel:DWORD src1_sel:WORD_1
	global_store_dwordx2 v[10:11], v[2:3], off offset:128
	v_mov_b64_e32 v[2:3], v[132:133]
	v_mov_b64_e32 v[4:5], v[134:135]
	v_pk_fma_f32 v[4:5], v[62:63], v[12:13], v[4:5] op_sel_hi:[1,0,1]
	v_pk_fma_f32 v[2:3], v[60:61], v[12:13], v[2:3] op_sel_hi:[1,0,1]
	v_and_b32_sdwa v8, v5, v174 dst_sel:DWORD dst_unused:UNUSED_PAD src0_sel:WORD_1 src1_sel:DWORD
	v_and_b32_sdwa v9, v3, v174 dst_sel:DWORD dst_unused:UNUSED_PAD src0_sel:WORD_1 src1_sel:DWORD
	v_and_b32_sdwa v6, v4, v174 dst_sel:DWORD dst_unused:UNUSED_PAD src0_sel:WORD_1 src1_sel:DWORD
	v_and_b32_sdwa v7, v2, v174 dst_sel:DWORD dst_unused:UNUSED_PAD src0_sel:WORD_1 src1_sel:DWORD
	v_add3_u32 v5, v5, v8, s9
	v_add3_u32 v3, v3, v9, s9
	v_add3_u32 v2, v2, v7, s9
	v_add3_u32 v4, v4, v6, s9
	v_and_b32_e32 v5, 0xffff0000, v5
	v_and_b32_e32 v6, 0xffff0000, v3
	v_or_b32_sdwa v3, v5, v4 dst_sel:DWORD dst_unused:UNUSED_PAD src0_sel:DWORD src1_sel:WORD_1
	v_or_b32_sdwa v2, v6, v2 dst_sel:DWORD dst_unused:UNUSED_PAD src0_sel:DWORD src1_sel:WORD_1
	global_store_dwordx2 v[10:11], v[2:3], off offset:160
	v_mov_b64_e32 v[2:3], v[136:137]
	v_mov_b64_e32 v[4:5], v[138:139]
	v_pk_fma_f32 v[4:5], v[58:59], v[12:13], v[4:5] op_sel_hi:[1,0,1]
	v_pk_fma_f32 v[2:3], v[56:57], v[12:13], v[2:3] op_sel_hi:[1,0,1]
	v_and_b32_sdwa v8, v5, v174 dst_sel:DWORD dst_unused:UNUSED_PAD src0_sel:WORD_1 src1_sel:DWORD
	v_and_b32_sdwa v9, v3, v174 dst_sel:DWORD dst_unused:UNUSED_PAD src0_sel:WORD_1 src1_sel:DWORD
	v_and_b32_sdwa v6, v4, v174 dst_sel:DWORD dst_unused:UNUSED_PAD src0_sel:WORD_1 src1_sel:DWORD
	v_and_b32_sdwa v7, v2, v174 dst_sel:DWORD dst_unused:UNUSED_PAD src0_sel:WORD_1 src1_sel:DWORD
	v_add3_u32 v5, v5, v8, s9
	v_add3_u32 v3, v3, v9, s9
	v_add3_u32 v2, v2, v7, s9
	v_add3_u32 v4, v4, v6, s9
	v_and_b32_e32 v5, 0xffff0000, v5
	v_and_b32_e32 v6, 0xffff0000, v3
	v_or_b32_sdwa v3, v5, v4 dst_sel:DWORD dst_unused:UNUSED_PAD src0_sel:DWORD src1_sel:WORD_1
	v_or_b32_sdwa v2, v6, v2 dst_sel:DWORD dst_unused:UNUSED_PAD src0_sel:DWORD src1_sel:WORD_1
	global_store_dwordx2 v[10:11], v[2:3], off offset:192
	v_mov_b64_e32 v[0:1], v[140:141]
	v_mov_b64_e32 v[2:3], v[142:143]
	v_pk_fma_f32 v[2:3], v[54:55], v[12:13], v[2:3] op_sel_hi:[1,0,1]
	v_pk_fma_f32 v[0:1], v[52:53], v[12:13], v[0:1] op_sel_hi:[1,0,1]
	v_and_b32_sdwa v6, v3, v174 dst_sel:DWORD dst_unused:UNUSED_PAD src0_sel:WORD_1 src1_sel:DWORD
	v_and_b32_sdwa v7, v1, v174 dst_sel:DWORD dst_unused:UNUSED_PAD src0_sel:WORD_1 src1_sel:DWORD
	v_and_b32_sdwa v4, v2, v174 dst_sel:DWORD dst_unused:UNUSED_PAD src0_sel:WORD_1 src1_sel:DWORD
	v_and_b32_sdwa v5, v0, v174 dst_sel:DWORD dst_unused:UNUSED_PAD src0_sel:WORD_1 src1_sel:DWORD
	v_add3_u32 v3, v3, v6, s9
	v_add3_u32 v1, v1, v7, s9
	v_add3_u32 v0, v0, v5, s9
	v_add3_u32 v2, v2, v4, s9
	v_and_b32_e32 v3, 0xffff0000, v3
	v_and_b32_e32 v4, 0xffff0000, v1
	v_or_b32_sdwa v1, v3, v2 dst_sel:DWORD dst_unused:UNUSED_PAD src0_sel:DWORD src1_sel:WORD_1
	v_or_b32_sdwa v0, v4, v0 dst_sel:DWORD dst_unused:UNUSED_PAD src0_sel:DWORD src1_sel:WORD_1
	global_store_dwordx2 v[10:11], v[0:1], off offset:224
	s_cbranch_scc0 .LBB0_1681
